# v062 with the W_IN late start of the 13-unit workgroups shortened from about 15 us to about 4 us (just past one epilogue, so XCD-mates still find each other's K-tiles in L2)
# speedup vs baseline: 1.0004x; 1.0004x over previous
.LBB0_194:
	s_cmp_lt_u32 s84, 0x80
	s_cbranch_scc1 .Lwin_nodelay
	s_cmp_eq_u32 s4, 3
	s_cbranch_scc1 .Lwin_nodelay
	s_sleep 127
